# removed the acquire invalidate inside the panel row-statistics exchange: every exchanged word is read with sc1 loads, nothing else crosses workgroups there
# speedup vs baseline: 1.0350x; 1.0075x over previous
; __device__ __forceinline__ float max3f(float a, float b, float c) { return fmaxf(fmaxf(a, b), c); }
; __device__ __forceinline__ void attn_qk(f32x16& p0, f32x16& p1, const bf16x8 (&kf)[12], const bf16x8 (&qf)[6]) {
;     const f32x16 zero = {0.f, 0.f, 0.f, 0.f, 0.f, 0.f, 0.f, 0.f, 0.f, 0.f, 0.f, 0.f, 0.f, 0.f, 0.f, 0.f};
; #pragma unroll
;     for (int ks = 0; ks < 6; ++ks) {
;         p0 = __builtin_amdgcn_mfma_f32_32x32x16_bf16(kf[2 * ks], qf[ks], ks == 0 ? zero : p0, 0, 0, 0);
;         p1 = __builtin_amdgcn_mfma_f32_32x32x16_bf16(kf[2 * ks + 1], qf[ks], ks == 0 ? zero : p1, 0, 0, 0);
;     }
; }
; __device__ __forceinline__ void attn_softmax(f32x16& p0, f32x16& p1, bf16x8 (&pb)[4], f32x16& o0, f32x16& o1, float& m_run, float& l_run) {
;     float mx = max3f(p0[0], p0[1], p1[0]), my = max3f(p0[2], p0[3], p1[1]);
;     mx = max3f(mx, p1[2], p1[3]);
; #pragma unroll
;     for (int r = 4; r < 16; r += 4) { mx = max3f(mx, p0[r], p0[r + 1]); my = max3f(my, p0[r + 2], p0[r + 3]); mx = max3f(mx, p1[r], p1[r + 1]); my = max3f(my, p1[r + 2], p1[r + 3]); }
;     mx = fmaxf(mx, my);
;     { auto rr = __builtin_amdgcn_permlane32_swap(__float_as_uint(mx), __float_as_uint(mx), false, false); mx = fmaxf(__uint_as_float(rr[0]), __uint_as_float(rr[1])); }
; __device__ __forceinline__ void attn_phase(LAS unsigned char* lds, const bf16_t* __restrict__ Q, const bf16_t* __restrict__ KN, const bf16_t* __restrict__ KR,
;                                            const bf16_t* __restrict__ VT, bf16_t* AO, int vcu, int G, int tid, int lane, int wave) {
;     ...
;                     attn_qk(a0, a1, kf, qf);
;                     attn_ldk(kf2, kA + 64 * KP * 2);
;                     __builtin_amdgcn_sched_barrier(0);
;                     attn_qk(b0, b1, kf2, qf);
;                     attn_softmax(a0, a1, pa, o0, o1, m_run, l_run);
.Lat_both:
	v_add_u32_e32 v1, s37, v222
	v_add_u32_e32 v225, s37, v223
	ds_read_b128 v[138:141], v1
	ds_read_b128 v[142:145], v1 offset:6656
	ds_read_b128 v[146:149], v1 offset:32
	ds_read_b128 v[150:153], v1 offset:6688
	ds_read_b128 v[154:157], v1 offset:64
	ds_read_b128 v[158:161], v1 offset:6720
	ds_read_b128 v[162:165], v1 offset:96
	ds_read_b128 v[166:169], v1 offset:6752
	s_waitcnt vmcnt(5)
	s_waitcnt lgkmcnt(7)
	v_mfma_f32_32x32x16_bf16 v[34:49], v[138:141], v[114:117], v[98:113]
	ds_read_b128 v[138:141], v1 offset:128
	s_waitcnt lgkmcnt(7)
	v_mfma_f32_32x32x16_bf16 v[50:65], v[142:145], v[114:117], v[98:113]
	ds_read_b128 v[142:145], v1 offset:6784
	s_waitcnt lgkmcnt(7)
	v_mfma_f32_32x32x16_bf16 v[34:49], v[146:149], v[118:121], v[34:49]
	ds_read_b128 v[146:149], v1 offset:160
	s_waitcnt lgkmcnt(7)
	v_mfma_f32_32x32x16_bf16 v[50:65], v[150:153], v[118:121], v[50:65]
	ds_read_b128 v[150:153], v1 offset:6816
	s_waitcnt lgkmcnt(7)
	v_mfma_f32_32x32x16_bf16 v[34:49], v[154:157], v[122:125], v[34:49]
	ds_read_b128 v[154:157], v1 offset:13312
	s_waitcnt lgkmcnt(7)
	v_mfma_f32_32x32x16_bf16 v[50:65], v[158:161], v[122:125], v[50:65]
	ds_read_b128 v[158:161], v1 offset:19968
	s_waitcnt lgkmcnt(7)
	v_mfma_f32_32x32x16_bf16 v[34:49], v[162:165], v[126:129], v[34:49]
	ds_read_b128 v[162:165], v1 offset:13344
	s_waitcnt lgkmcnt(7)
	v_mfma_f32_32x32x16_bf16 v[50:65], v[166:169], v[126:129], v[50:65]
	ds_read_b128 v[166:169], v1 offset:20000
	s_waitcnt lgkmcnt(7)
	v_mfma_f32_32x32x16_bf16 v[34:49], v[138:141], v[130:133], v[34:49]
	ds_read_b128 v[138:141], v1 offset:13376
	s_waitcnt lgkmcnt(7)
	v_mfma_f32_32x32x16_bf16 v[50:65], v[142:145], v[130:133], v[50:65]
	ds_read_b128 v[142:145], v1 offset:20032
	s_waitcnt lgkmcnt(7)
	v_mfma_f32_32x32x16_bf16 v[34:49], v[146:149], v[134:137], v[34:49]
	ds_read_b128 v[146:149], v1 offset:13408
	s_waitcnt lgkmcnt(7)
	v_mfma_f32_32x32x16_bf16 v[50:65], v[150:153], v[134:137], v[50:65]
	ds_read_b128 v[150:153], v1 offset:20064
	s_waitcnt lgkmcnt(7)
	v_mfma_f32_32x32x16_bf16 v[66:81], v[154:157], v[114:117], v[98:113]
	ds_read_b128 v[154:157], v1 offset:13440
	s_waitcnt lgkmcnt(7)
	v_mfma_f32_32x32x16_bf16 v[82:97], v[158:161], v[114:117], v[98:113]
	ds_read_b128 v[158:161], v1 offset:20096
	s_waitcnt lgkmcnt(7)
	v_mfma_f32_32x32x16_bf16 v[66:81], v[162:165], v[118:121], v[66:81]
	ds_read_b128 v[162:165], v1 offset:13472
	s_waitcnt lgkmcnt(7)
	v_mfma_f32_32x32x16_bf16 v[82:97], v[166:169], v[118:121], v[82:97]
	ds_read_b128 v[166:169], v1 offset:20128
	v_max3_f32 v249, v34, v35, v36
	v_max3_f32 v1, v50, v51, v52
	v_max3_f32 v249, v249, v37, v38
	v_max3_f32 v1, v1, v53, v54
	v_max3_f32 v249, v249, v39, v40
	v_max3_f32 v1, v1, v55, v56
	v_max3_f32 v249, v249, v41, v42
	s_waitcnt lgkmcnt(7)
	v_mfma_f32_32x32x16_bf16 v[66:81], v[138:141], v[122:125], v[66:81]
	ds_read_b128 v[170:173], v225 offset:26624
	v_max3_f32 v1, v1, v57, v58
	v_max3_f32 v249, v249, v43, v44
	v_max3_f32 v1, v1, v59, v60
	v_max3_f32 v249, v249, v45, v46
	v_max3_f32 v1, v1, v61, v62
	v_max3_f32 v249, v249, v47, v48
	v_max3_f32 v1, v1, v63, v64
	s_waitcnt lgkmcnt(7)
	v_mfma_f32_32x32x16_bf16 v[82:97], v[142:145], v[122:125], v[82:97]
	ds_read_b128 v[174:177], v225 offset:35328
	v_max_f32_e32 v249, v249, v49
	v_max_f32_e32 v1, v1, v65
	v_max_f32_e32 v249, v249, v1
	v_mov_b32_e32 v1, v249
	s_nop 1
	v_permlane32_swap_b32_e32 v249, v1
	v_max_f32_e32 v249, v249, v1
	s_waitcnt lgkmcnt(7)
	v_mfma_f32_32x32x16_bf16 v[66:81], v[146:149], v[126:129], v[66:81]
	ds_read_b128 v[178:181], v225 offset:26656
	v_cmp_lt_f32_e32 vcc, s26, v249
	s_cbranch_vccnz .Lat_slow_A2
; #define LAS __attribute__((address_space(3)))
; __device__ __forceinline__ void attn_phase(LAS unsigned char* lds, const bf16_t* __restrict__ Q, const bf16_t* __restrict__ KN, const bf16_t* __restrict__ KR,
;                                            const bf16_t* __restrict__ VT, bf16_t* AO, int vcu, int G, int tid, int lane, int wave) {
;     ...
;                     attn_softmax(a0, a1, pa, o0, o1, m_run, l_run);
;                     attn_ldv(vf, vA);
;                     __builtin_amdgcn_sched_barrier(0);
;                     PREFETCH_NEXT();
;                     attn_ldv(vf2, vA + 128);
;                     __builtin_amdgcn_sched_barrier(0);
;                     attn_pv(vf, pa, o0, o1);
;                     attn_softmax(b0, b1, pb2, o0, o1, m_run, l_run);
;                     __builtin_amdgcn_sched_barrier(0);
;                     attn_pv(vf2, pb2, o0, o1);
;     ...
;                 if (more) { LAS unsigned char* nb = lds + ((t + 1) & 1) * BUF;
;                     *(LAS u32x4*)(nb + kdst) = gk0; *(LAS u32x4*)(nb + kdst + 64 * KP * 2) = gk1; *(LAS u32x4*)(nb + rdst) = gr; *(LAS u32x4*)(nb + vdst) = gv0; *(LAS u32x4*)(nb + vdst + 128) = gv1; }
.Lat_fast_A2:
	v_exp_f32_e32 v34, v34
	v_exp_f32_e32 v50, v50
	v_exp_f32_e32 v35, v35
	v_exp_f32_e32 v51, v51
	v_exp_f32_e32 v36, v36
	v_exp_f32_e32 v52, v52
	s_waitcnt lgkmcnt(7)
	v_mfma_f32_32x32x16_bf16 v[82:97], v[150:153], v[126:129], v[82:97]
	ds_read_b128 v[182:185], v225 offset:35360
	v_exp_f32_e32 v37, v37
	v_exp_f32_e32 v53, v53
	v_exp_f32_e32 v38, v38
	v_exp_f32_e32 v54, v54
	v_exp_f32_e32 v39, v39
	v_exp_f32_e32 v55, v55
	v_exp_f32_e32 v40, v40
	s_waitcnt lgkmcnt(7)
	v_mfma_f32_32x32x16_bf16 v[66:81], v[154:157], v[130:133], v[66:81]
	ds_read_b128 v[186:189], v225 offset:26688
	v_exp_f32_e32 v56, v56
	v_exp_f32_e32 v41, v41
	v_exp_f32_e32 v57, v57
	v_exp_f32_e32 v42, v42
	v_exp_f32_e32 v58, v58
	v_exp_f32_e32 v43, v43
	v_exp_f32_e32 v59, v59
	s_waitcnt lgkmcnt(7)
	v_mfma_f32_32x32x16_bf16 v[82:97], v[158:161], v[130:133], v[82:97]
	ds_read_b128 v[190:193], v225 offset:35392
	v_exp_f32_e32 v44, v44
	v_exp_f32_e32 v60, v60
	v_exp_f32_e32 v45, v45
	v_exp_f32_e32 v61, v61
	v_exp_f32_e32 v46, v46
	v_exp_f32_e32 v62, v62
	v_exp_f32_e32 v47, v47
	s_waitcnt lgkmcnt(7)
	v_mfma_f32_32x32x16_bf16 v[66:81], v[162:165], v[134:137], v[66:81]
	v_exp_f32_e32 v63, v63
	v_exp_f32_e32 v48, v48
	v_exp_f32_e32 v64, v64
	v_exp_f32_e32 v49, v49
	v_exp_f32_e32 v65, v65
	v_pk_add_f32 v[250:251], v[34:35], v[36:37]
	v_pk_add_f32 v[252:253], v[50:51], v[52:53]
	s_waitcnt lgkmcnt(6)
	v_mfma_f32_32x32x16_bf16 v[82:97], v[166:169], v[134:137], v[82:97]
	v_pk_add_f32 v[250:251], v[250:251], v[38:39]
	v_pk_add_f32 v[252:253], v[252:253], v[54:55]
	v_pk_add_f32 v[250:251], v[250:251], v[40:41]
	v_pk_add_f32 v[252:253], v[252:253], v[56:57]
	v_pk_add_f32 v[250:251], v[250:251], v[42:43]
	v_pk_add_f32 v[252:253], v[252:253], v[58:59]
	v_pk_add_f32 v[250:251], v[250:251], v[44:45]
	v_pk_add_f32 v[252:253], v[252:253], v[60:61]
	v_pk_add_f32 v[250:251], v[250:251], v[46:47]
	v_pk_add_f32 v[252:253], v[252:253], v[62:63]
	v_pk_add_f32 v[250:251], v[250:251], v[48:49]
	v_pk_add_f32 v[252:253], v[252:253], v[64:65]
	v_pk_add_f32 v[250:251], v[250:251], v[252:253]
	v_add_f32_e32 v1, v250, v251
	v_add_f32_e32 v227, v227, v1
	v_cvt_pk_bf16_f32 v34, v34, v35
	v_cvt_pk_bf16_f32 v35, v36, v37
	v_cvt_pk_bf16_f32 v36, v38, v39
	v_cvt_pk_bf16_f32 v37, v40, v41
	v_cvt_pk_bf16_f32 v42, v42, v43
	v_cvt_pk_bf16_f32 v43, v44, v45
	v_cvt_pk_bf16_f32 v44, v46, v47
	v_cvt_pk_bf16_f32 v45, v48, v49
	v_cvt_pk_bf16_f32 v50, v50, v51
	v_cvt_pk_bf16_f32 v51, v52, v53
	v_cvt_pk_bf16_f32 v52, v54, v55
	v_cvt_pk_bf16_f32 v53, v56, v57
	v_cvt_pk_bf16_f32 v58, v58, v59
	v_cvt_pk_bf16_f32 v59, v60, v61
	v_cvt_pk_bf16_f32 v60, v62, v63
	v_cvt_pk_bf16_f32 v61, v64, v65
	s_waitcnt lgkmcnt(5)
	v_mfma_f32_32x32x16_bf16 v[2:17], v[170:173], v[34:37], v[2:17]
	ds_read_b128 v[170:173], v225 offset:26720
	v_max3_f32 v249, v66, v67, v68
	v_max3_f32 v1, v82, v83, v84
	v_max3_f32 v249, v249, v69, v70
	v_max3_f32 v1, v1, v85, v86
	v_max3_f32 v249, v249, v71, v72
	v_max3_f32 v1, v1, v87, v88
	v_max3_f32 v249, v249, v73, v74
	v_max3_f32 v1, v1, v89, v90
	s_waitcnt lgkmcnt(5)
	v_mfma_f32_32x32x16_bf16 v[18:33], v[174:177], v[34:37], v[18:33]
	ds_read_b128 v[174:177], v225 offset:35424
	s_waitcnt vmcnt(0)
	v_add_u32_e32 v226, s38, v219
	ds_write_b128 v226, v[228:231]
	v_max3_f32 v249, v249, v75, v76
	v_max3_f32 v1, v1, v91, v92
	v_max3_f32 v249, v249, v77, v78
	v_max3_f32 v1, v1, v93, v94
	v_max3_f32 v249, v249, v79, v80
	v_max3_f32 v1, v1, v95, v96
	v_max_f32_e32 v249, v249, v81
	v_max_f32_e32 v1, v1, v97
	s_waitcnt lgkmcnt(6)
	v_mfma_f32_32x32x16_bf16 v[2:17], v[178:181], v[42:45], v[2:17]
	ds_read_b128 v[178:181], v225 offset:26752
	ds_write_b128 v226, v[232:235] offset:13312
	v_max_f32_e32 v249, v249, v1
	v_mov_b32_e32 v1, v249
	s_nop 1
	v_permlane32_swap_b32_e32 v249, v1
	v_max_f32_e32 v249, v249, v1
	s_cmp_lg_u32 s6, 0
	s_cbranch_scc1 .Lat_fix_B

; __device__ __forceinline__ void attn_pv(const bf16x8 (&vf)[8], const bf16x8 (&pb)[4], f32x16& o0, f32x16& o1) {
; #pragma unroll
;     for (int s = 0; s < 4; ++s) {
;         o0 = __builtin_amdgcn_mfma_f32_32x32x16_bf16(vf[2 * s], pb[s], o0, 0, 0, 0);
;         o1 = __builtin_amdgcn_mfma_f32_32x32x16_bf16(vf[2 * s + 1], pb[s], o1, 0, 0, 0);
;     }
; }
; __device__ __forceinline__ void attn_phase(LAS unsigned char* lds, const bf16_t* __restrict__ Q, const bf16_t* __restrict__ KN, const bf16_t* __restrict__ KR,
;                                            const bf16_t* __restrict__ VT, bf16_t* AO, int vcu, int G, int tid, int lane, int wave) {
;     ...
;                     attn_softmax(b0, b1, pb2, o0, o1, m_run, l_run);
;                     __builtin_amdgcn_sched_barrier(0);
;                     attn_pv(vf2, pb2, o0, o1);
.Lat_fast_B2:
	v_exp_f32_e32 v66, v66
	s_waitcnt lgkmcnt(7)
	v_mfma_f32_32x32x16_bf16 v[18:33], v[182:185], v[42:45], v[18:33]
	ds_read_b128 v[182:185], v225 offset:35456
	v_add_u32_e32 v226, s38, v220
	ds_write_b128 v226, v[236:239]
	v_exp_f32_e32 v82, v82
	v_exp_f32_e32 v67, v67
	v_exp_f32_e32 v83, v83
	v_exp_f32_e32 v68, v68
	v_exp_f32_e32 v84, v84
	v_exp_f32_e32 v69, v69
	v_exp_f32_e32 v85, v85
	v_exp_f32_e32 v70, v70
	s_waitcnt lgkmcnt(8)
	v_mfma_f32_32x32x16_bf16 v[2:17], v[186:189], v[50:53], v[2:17]
	ds_read_b128 v[186:189], v225 offset:26784
	v_add_u32_e32 v226, s38, v221
	ds_write_b128 v226, v[240:243] offset:26624
	v_exp_f32_e32 v86, v86
	v_exp_f32_e32 v71, v71
	v_exp_f32_e32 v87, v87
	v_exp_f32_e32 v72, v72
	v_exp_f32_e32 v88, v88
	v_exp_f32_e32 v73, v73
	v_exp_f32_e32 v89, v89
	v_exp_f32_e32 v74, v74
	s_waitcnt lgkmcnt(9)
	v_mfma_f32_32x32x16_bf16 v[18:33], v[190:193], v[50:53], v[18:33]
	ds_read_b128 v[190:193], v225 offset:35488
	ds_write_b128 v226, v[244:247] offset:26752
	v_exp_f32_e32 v90, v90
	v_exp_f32_e32 v75, v75
	v_exp_f32_e32 v91, v91
	v_exp_f32_e32 v76, v76
	v_exp_f32_e32 v92, v92
	v_exp_f32_e32 v77, v77
	v_exp_f32_e32 v93, v93
	v_exp_f32_e32 v78, v78
	s_waitcnt lgkmcnt(10)
	v_mfma_f32_32x32x16_bf16 v[2:17], v[170:173], v[58:61], v[2:17]
	ds_read_b128 v[170:173], v225 offset:26816
	v_exp_f32_e32 v94, v94
	v_exp_f32_e32 v79, v79
	v_exp_f32_e32 v95, v95
	v_exp_f32_e32 v80, v80
	v_exp_f32_e32 v96, v96
	v_exp_f32_e32 v81, v81
	v_exp_f32_e32 v97, v97
	v_pk_add_f32 v[250:251], v[66:67], v[68:69]
	s_waitcnt lgkmcnt(10)
	v_mfma_f32_32x32x16_bf16 v[18:33], v[174:177], v[58:61], v[18:33]
	ds_read_b128 v[174:177], v225 offset:35520
	v_pk_add_f32 v[252:253], v[82:83], v[84:85]
	v_pk_add_f32 v[250:251], v[250:251], v[70:71]
	v_pk_add_f32 v[252:253], v[252:253], v[86:87]
	v_pk_add_f32 v[250:251], v[250:251], v[72:73]
	v_pk_add_f32 v[252:253], v[252:253], v[88:89]
	v_pk_add_f32 v[250:251], v[250:251], v[74:75]
	v_pk_add_f32 v[252:253], v[252:253], v[90:91]
	v_pk_add_f32 v[250:251], v[250:251], v[76:77]
	v_pk_add_f32 v[252:253], v[252:253], v[92:93]
	v_pk_add_f32 v[250:251], v[250:251], v[78:79]
	v_pk_add_f32 v[252:253], v[252:253], v[94:95]
	v_pk_add_f32 v[250:251], v[250:251], v[80:81]
	v_pk_add_f32 v[252:253], v[252:253], v[96:97]
	v_pk_add_f32 v[250:251], v[250:251], v[252:253]
	v_add_f32_e32 v1, v250, v251
	v_add_f32_e32 v227, v227, v1
	v_cvt_pk_bf16_f32 v66, v66, v67
	v_cvt_pk_bf16_f32 v67, v68, v69
	v_cvt_pk_bf16_f32 v68, v70, v71
	v_cvt_pk_bf16_f32 v69, v72, v73
	v_cvt_pk_bf16_f32 v74, v74, v75
	v_cvt_pk_bf16_f32 v75, v76, v77
	v_cvt_pk_bf16_f32 v76, v78, v79
	v_cvt_pk_bf16_f32 v77, v80, v81
	v_cvt_pk_bf16_f32 v82, v82, v83
	v_cvt_pk_bf16_f32 v83, v84, v85
	v_cvt_pk_bf16_f32 v84, v86, v87
	v_cvt_pk_bf16_f32 v85, v88, v89
	v_cvt_pk_bf16_f32 v90, v90, v91
	v_cvt_pk_bf16_f32 v91, v92, v93
	v_cvt_pk_bf16_f32 v92, v94, v95
	v_cvt_pk_bf16_f32 v93, v96, v97
	s_cmp_lg_u32 s7, 0
	s_cbranch_scc1 .Lat_resc_O
.Lat_resc_O_ret:
	s_waitcnt lgkmcnt(9)
	v_mfma_f32_32x32x16_bf16 v[2:17], v[178:181], v[66:69], v[2:17]
	ds_read_b128 v[178:181], v225 offset:26848
	s_waitcnt lgkmcnt(8)
	v_mfma_f32_32x32x16_bf16 v[18:33], v[182:185], v[66:69], v[18:33]
	ds_read_b128 v[182:185], v225 offset:35552
	s_waitcnt lgkmcnt(7)
	v_mfma_f32_32x32x16_bf16 v[2:17], v[186:189], v[74:77], v[2:17]
	s_waitcnt lgkmcnt(5)
	v_mfma_f32_32x32x16_bf16 v[18:33], v[190:193], v[74:77], v[18:33]
	s_waitcnt lgkmcnt(3)
	v_mfma_f32_32x32x16_bf16 v[2:17], v[170:173], v[82:85], v[2:17]
	s_waitcnt lgkmcnt(2)
	v_mfma_f32_32x32x16_bf16 v[18:33], v[174:177], v[82:85], v[18:33]
	s_waitcnt lgkmcnt(1)
	v_mfma_f32_32x32x16_bf16 v[2:17], v[178:181], v[90:93], v[2:17]
	s_waitcnt lgkmcnt(0)
	v_mfma_f32_32x32x16_bf16 v[18:33], v[182:185], v[90:93], v[18:33]
	s_branch .Lat_nostage

; __device__ __forceinline__ void attn_softmax(f32x16& p0, f32x16& p1, bf16x8 (&pb)[4], f32x16& o0, f32x16& o1, float& m_run, float& l_run) {
;     ...
;     const float m_new = fmaxf(m_run, mx);
;     const float alpha = __builtin_amdgcn_exp2f(m_run - m_new);
;     m_run = m_new;
;     p0 = p0 - m_new; p1 = p1 - m_new;
; #pragma unroll
;     for (int r = 0; r < 16; ++r) { p0[r] = __builtin_amdgcn_exp2f(p0[r]); p1[r] = __builtin_amdgcn_exp2f(p1[r]); }
;     f32x16 sm = p0 + p1;
;     f32x2v s2 = (f32x2v){sm[0], sm[1]} + (f32x2v){sm[2], sm[3]};
; #pragma unroll
;     for (int r = 4; r < 16; r += 2) s2 += (f32x2v){sm[r], sm[r + 1]};
;     l_run = l_run * alpha + (s2[0] + s2[1]);
;     o0 = o0 * alpha; o1 = o1 * alpha;
.Lat_slow_B2:
	s_nop 15
	v_max_f32_e32 v250, s27, v249
	v_add_f32_e32 v248, v248, v250
	v_sub_f32_e32 v251, 0, v248
	v_mov_b32_e32 v98, v251
	v_mov_b32_e32 v99, v251
	v_mov_b32_e32 v100, v251
	v_mov_b32_e32 v101, v251
	v_mov_b32_e32 v102, v251
	v_mov_b32_e32 v103, v251
	v_mov_b32_e32 v104, v251
	v_mov_b32_e32 v105, v251
	v_mov_b32_e32 v106, v251
	v_mov_b32_e32 v107, v251
	v_mov_b32_e32 v108, v251
	v_mov_b32_e32 v109, v251
	v_mov_b32_e32 v110, v251
	v_mov_b32_e32 v111, v251
	v_mov_b32_e32 v112, v251
	v_mov_b32_e32 v113, v251
	v_sub_f32_e32 v66, v66, v250
	v_sub_f32_e32 v67, v67, v250
	v_sub_f32_e32 v68, v68, v250
	v_sub_f32_e32 v69, v69, v250
	v_sub_f32_e32 v70, v70, v250
	v_sub_f32_e32 v71, v71, v250
	v_sub_f32_e32 v72, v72, v250
	v_sub_f32_e32 v73, v73, v250
	v_sub_f32_e32 v74, v74, v250
	v_sub_f32_e32 v75, v75, v250
	v_sub_f32_e32 v76, v76, v250
	v_sub_f32_e32 v77, v77, v250
	v_sub_f32_e32 v78, v78, v250
	v_sub_f32_e32 v79, v79, v250
	v_sub_f32_e32 v80, v80, v250
	v_sub_f32_e32 v81, v81, v250
	v_sub_f32_e32 v82, v82, v250
	v_sub_f32_e32 v83, v83, v250
	v_sub_f32_e32 v84, v84, v250
	v_sub_f32_e32 v85, v85, v250
	v_sub_f32_e32 v86, v86, v250
	v_sub_f32_e32 v87, v87, v250
	v_sub_f32_e32 v88, v88, v250
	v_sub_f32_e32 v89, v89, v250
	v_sub_f32_e32 v90, v90, v250
	v_sub_f32_e32 v91, v91, v250
	v_sub_f32_e32 v92, v92, v250
	v_sub_f32_e32 v93, v93, v250
	v_sub_f32_e32 v94, v94, v250
	v_sub_f32_e32 v95, v95, v250
	v_sub_f32_e32 v96, v96, v250
	v_sub_f32_e32 v97, v97, v250
	v_sub_f32_e32 v252, 0, v250
	v_min_f32_e32 v252, 0x42800000, v252
	v_exp_f32_e32 v252, v252
	s_mov_b32 s26, 0x41a00000
	s_mov_b32 s27, 0
	v_mul_f32_e32 v227, v227, v252
	v_mov_b32_e32 v218, v252
	s_mov_b32 s7, 1
	s_nop 1
	s_branch .Lat_fast_B2
.Lat_resc_O:
	s_nop 15
	s_mov_b32 s7, 0
	v_mul_f32_e32 v2, v2, v218
	v_mul_f32_e32 v3, v3, v218
	v_mul_f32_e32 v4, v4, v218
	v_mul_f32_e32 v5, v5, v218
	v_mul_f32_e32 v6, v6, v218
	v_mul_f32_e32 v7, v7, v218
	v_mul_f32_e32 v8, v8, v218
	v_mul_f32_e32 v9, v9, v218
	v_mul_f32_e32 v10, v10, v218
	v_mul_f32_e32 v11, v11, v218
	v_mul_f32_e32 v12, v12, v218
	v_mul_f32_e32 v13, v13, v218
	v_mul_f32_e32 v14, v14, v218
	v_mul_f32_e32 v15, v15, v218
	v_mul_f32_e32 v16, v16, v218
	v_mul_f32_e32 v17, v17, v218
	v_mul_f32_e32 v18, v18, v218
	v_mul_f32_e32 v19, v19, v218
	v_mul_f32_e32 v20, v20, v218
	v_mul_f32_e32 v21, v21, v218
	v_mul_f32_e32 v22, v22, v218
	v_mul_f32_e32 v23, v23, v218
	v_mul_f32_e32 v24, v24, v218
	v_mul_f32_e32 v25, v25, v218
	v_mul_f32_e32 v26, v26, v218
	v_mul_f32_e32 v27, v27, v218
	v_mul_f32_e32 v28, v28, v218
	v_mul_f32_e32 v29, v29, v218
	v_mul_f32_e32 v30, v30, v218
	v_mul_f32_e32 v31, v31, v218
	v_mul_f32_e32 v32, v32, v218
	v_mul_f32_e32 v33, v33, v218
	s_nop 1
	s_branch .Lat_resc_O_ret

;     __device__ __forceinline__ void run(const f32x4 (&v)[2][2][4][2], const Unit& u, int wr, int wc, int fr, int fq, PG8_LAS unsigned char* lds, int wid, int lane) const {
;     ...
;             __builtin_amdgcn_fence(__ATOMIC_ACQUIRE, "agent");
;         }
;         asm volatile("s_waitcnt vmcnt(0) lgkmcnt(0)" ::: "memory"); __builtin_amdgcn_s_barrier(); asm volatile("" ::: "memory");
;         if (lane < 32) {
;             const float* slot = xbuf + (size_t)(pmg * BM + row) * 4; float t = 0.f;
; #pragma unroll
;             for (int k = 0; k < 4; ++k) t += __hip_atomic_load(slot + k, __ATOMIC_RELAXED, __HIP_MEMORY_SCOPE_AGENT);
;             S[row] = rsqrtf(t * (1.0f / 1024.0f) + eps);
;         }
.LBB0_787:
	s_waitcnt lgkmcnt(0)
.LBB0_788:
	s_waitcnt vmcnt(0) lgkmcnt(0)
	s_barrier
	v_lshl_add_u32 v152, v129, 2, 0
	s_and_saveexec_b64 s[54:55], s[8:9]
	s_cbranch_execz .LBB0_790
	v_ashrrev_i32_e32 v145, 31, v144
	v_lshl_add_u64 v[128:129], v[144:145], 4, s[52:53]
	s_waitcnt lgkmcnt(0)
	global_load_dword v130, v[128:129], off sc1
	global_load_dword v131, v[128:129], off offset:4 sc1
	global_load_dword v132, v[128:129], off offset:8 sc1
	s_nop 0
	global_load_dword v128, v[128:129], off offset:12 sc1
	s_waitcnt vmcnt(0)
	v_add_f32_e32 v129, 0, v130
	v_add_f32_e32 v129, v129, v131
	v_add_f32_e32 v129, v129, v132
	v_add_f32_e32 v128, v129, v128
	v_fmamk_f32 v128, v128, 0x3a800000, v184
	v_mul_f32_e32 v129, 0x4b800000, v128
	v_cmp_gt_f32_e32 vcc, s67, v128
	s_nop 1
	v_cndmask_b32_e32 v128, v128, v129, vcc
	v_rsq_f32_e32 v128, v128
	s_nop 0
	v_mul_f32_e32 v129, 0x45800000, v128
	v_cndmask_b32_e32 v128, v128, v129, vcc
	ds_write_b32 v152, v128 offset:4096

;     __device__ __forceinline__ void run(const f32x4 (&v)[2][2][4][2], const Unit& u, int wr, int wc, int fr, int fq, PG8_LAS unsigned char* lds, int wid, int lane) const {
;     ...
;             __builtin_amdgcn_fence(__ATOMIC_ACQUIRE, "agent");
;         }
;         asm volatile("s_waitcnt vmcnt(0) lgkmcnt(0)" ::: "memory"); __builtin_amdgcn_s_barrier(); asm volatile("" ::: "memory");
;         if (lane < 32) {
;             const float* slot = xbuf + (size_t)(pmg * BM + row) * 4; float t = 0.f;
; #pragma unroll
;             for (int k = 0; k < 4; ++k) t += __hip_atomic_load(slot + k, __ATOMIC_RELAXED, __HIP_MEMORY_SCOPE_AGENT);
;             S[row] = rsqrtf(t * (1.0f / 1024.0f) + eps);
;         }
.LBB0_820:
	s_waitcnt lgkmcnt(0)
.LBB0_821:
	s_waitcnt vmcnt(0) lgkmcnt(0)
	s_barrier
	s_and_saveexec_b64 s[10:11], s[8:9]
	s_cbranch_execz .LBB0_735
	v_ashrrev_i32_e32 v145, 31, v144
	s_waitcnt lgkmcnt(0)
	v_lshl_add_u64 v[128:129], v[144:145], 4, s[6:7]
	global_load_dword v130, v[128:129], off sc1
	global_load_dword v131, v[128:129], off offset:4 sc1
	global_load_dword v132, v[128:129], off offset:8 sc1
	s_nop 0
	global_load_dword v128, v[128:129], off offset:12 sc1
	s_waitcnt vmcnt(3)
	v_add_f32_e32 v129, 0, v130
	s_waitcnt vmcnt(2)
	v_add_f32_e32 v129, v129, v131
	s_waitcnt vmcnt(1)
	v_add_f32_e32 v129, v129, v132
	s_waitcnt vmcnt(0)
	v_add_f32_e32 v128, v129, v128
	v_fmamk_f32 v128, v128, 0x3a800000, v184
	v_mul_f32_e32 v129, 0x4b800000, v128
	v_cmp_gt_f32_e32 vcc, s67, v128
	s_nop 1
	v_cndmask_b32_e32 v128, v128, v129, vcc
	v_rsq_f32_e32 v128, v128
	s_nop 0
	v_mul_f32_e32 v129, 0x45800000, v128
	v_cndmask_b32_e32 v128, v128, v129, vcc
	ds_write_b32 v152, v128 offset:4096
	s_branch .LBB0_735

;     __device__ __forceinline__ void run(const f32x4 (&v)[2][2][4][2], const Unit& u, int wr, int wc, int fr, int fq, PG8_LAS unsigned char* lds, int wid, int lane) const {
;     ...
;             __builtin_amdgcn_fence(__ATOMIC_ACQUIRE, "agent");
;         }
;         asm volatile("s_waitcnt vmcnt(0) lgkmcnt(0)" ::: "memory"); __builtin_amdgcn_s_barrier(); asm volatile("" ::: "memory");
;         if (lane < 32) {
;             const float* slot = xbuf + (size_t)(pmg * BM + row) * 4; float t = 0.f;
; #pragma unroll
;             for (int k = 0; k < 4; ++k) t += __hip_atomic_load(slot + k, __ATOMIC_RELAXED, __HIP_MEMORY_SCOPE_AGENT);
;             S[row] = rsqrtf(t * (1.0f / 1024.0f) + eps);
;         }
.LBB0_1169:
.LBB0_1170:
	s_waitcnt vmcnt(0) lgkmcnt(0)
	s_barrier
	s_and_saveexec_b64 s[10:11], s[6:7]
	s_cbranch_execz .LBB0_1113
	s_waitcnt lgkmcnt(0)
	v_ashrrev_i32_e32 v129, 31, v128
	v_lshl_add_u64 v[128:129], v[128:129], 4, s[8:9]
	global_load_dword v130, v[128:129], off sc1
	global_load_dword v132, v[128:129], off offset:4 sc1
	global_load_dword v133, v[128:129], off offset:8 sc1
	s_nop 0
	global_load_dword v128, v[128:129], off offset:12 sc1
	s_waitcnt vmcnt(0)
	v_add_f32_e32 v129, 0, v130
	v_add_f32_e32 v129, v129, v132
	v_add_f32_e32 v129, v129, v133
	v_add_f32_e32 v128, v129, v128
	v_fmamk_f32 v128, v128, 0x3a800000, v154
	v_mul_f32_e32 v129, 0x4b800000, v128
	v_cmp_gt_f32_e32 vcc, s48, v128
	s_nop 1
	v_cndmask_b32_e32 v128, v128, v129, vcc
	v_rsq_f32_e32 v128, v128
	s_nop 0
	v_mul_f32_e32 v129, 0x45800000, v128
	v_cndmask_b32_e32 v128, v128, v129, vcc
	v_lshl_add_u32 v129, v131, 2, 0
	ds_write_b32 v129, v128 offset:4096
	s_branch .LBB0_1113
